# hyena filter copies with all loads in flight; adaLN-mod prep items moved to less loaded virtual blocks
# speedup vs baseline: 1.0323x; 1.0106x over previous
; #define VBID ((int)blockIdx.x * 2 + vhalf())
; DEV void phase_prep(const Params& p, char* smem) {
;   if (blockIdx.x == 0 && threadIdx.x < 64) ((unsigned*)(p.ws + OFF_CNT))[threadIdx.x] = 0u;
;   for (int it = VBID; it < 4096 + 192; it += NVB) {
;     if (it < 1536) prep_transpose_tile(p.in[I_WIN], 1024, 6144, (u16*)(p.ws + OFF_WIN), it, smem);
;     else if (it < 1792) prep_transpose_tile(p.in[I_WBR], 1024, 1024, (u16*)(p.ws + OFF_WBR), it - 1536, smem);
;     else if (it < 2048) prep_transpose_tile(p.in[I_WOUT], 1024, 1024, (u16*)(p.ws + OFF_WOUT), it - 1792, smem);
;     else if (it < 3072) prep_transpose_tile(p.in[I_WFF1], 1024, 4096, (u16*)(p.ws + OFF_WFF1), it - 2048, smem);
;     else if (it < 4096) prep_transpose_tile(p.in[I_WFF2], 4096, 1024, (u16*)(p.ws + OFF_WFF2), it - 3072, smem);
;     else prep_mod_item(p, it - 4096, smem);
;   }
.LBB0_9:
	s_add_i32 s22, s22, s23
	s_add_i32 s24, s24, s25
	s_add_i32 s27, s27, s25
	s_cmpk_lt_i32 s22, 0x1000
	s_cbranch_scc1 .Lprep_nomod
	s_cmpk_lt_i32 s22, 0x1100
	s_cbranch_scc1 .LBB0_38
	s_sub_i32 s22, s22, 0x100
	s_sub_i32 s24, s24, 0x2000
	s_sub_i32 s27, s27, 0x2000
.Lprep_nomod:
	s_cmpk_lt_i32 s22, 0x10c0
	s_cbranch_scc0 .LBB0_38

; template <int BG>
; DEV void hyena_item_mfma(const Params& p, int g, int item, char* smem, int half) {
;     ...
; #pragma unroll 4
;     for (int e = tid; e < 2 * L / 8; e += 256) {
;       const uint4 v = ((const uint4*)RK)[e];
;       const unsigned nx = (8 * e + 8 < 2 * L) ? (unsigned)RK[8 * e + 8] : 0u;
;       uint4 o;
;       o.x = (v.x >> 16) | (v.y << 16);
;       o.y = (v.y >> 16) | (v.z << 16);
;       o.z = (v.z >> 16) | (v.w << 16);
;       o.w = (v.w >> 16) | (nx << 16);
;       ((uint4*)(smem + RK1))[e] = o;
;     }
.LBB0_732:
	v_add_co_u32_e32 v10, vcc, 0x400, v10
	s_xor_b64 s[12:13], vcc, -1
	s_add_u32 s4, s4, 0x4000
	s_addc_u32 s5, s5, 0
	s_add_u32 s10, s10, 0xffffc000
	s_mov_b32 s20, 0x1000706
	s_addc_u32 s11, s11, 0
	s_waitcnt vmcnt(0)
	v_perm_b32 v0, v16, v17, s20
	v_perm_b32 v1, v17, v18, s20
	v_perm_b32 v2, v18, v19, s20
	v_perm_b32 v3, v19, v32, s20
	ds_write_b128 v9, v[0:3]
	v_perm_b32 v0, v20, v21, s20
	v_perm_b32 v1, v21, v22, s20
	v_perm_b32 v2, v22, v23, s20
	v_perm_b32 v3, v23, v33, s20
	ds_write_b128 v9, v[0:3] offset:4096
	v_perm_b32 v0, v24, v25, s20
	v_perm_b32 v1, v25, v26, s20
	v_perm_b32 v2, v26, v27, s20
	v_perm_b32 v3, v27, v34, s20
	ds_write_b128 v9, v[0:3] offset:8192
	v_perm_b32 v0, v28, v29, s20
	v_perm_b32 v1, v29, v30, s20
	v_perm_b32 v2, v30, v31, s20
	v_perm_b32 v3, v31, v35, s20
	ds_write_b128 v9, v[0:3] offset:12288
	s_and_b64 s[12:13], exec, s[12:13]
	s_or_b64 s[8:9], s[12:13], s[8:9]
	v_add_u32_e32 v9, 0x4000, v9
	s_andn2_b64 exec, exec, s[8:9]
	s_cbranch_execz .LBB0_735
.LBB0_733:
	v_lshl_add_u64 v[6:7], s[4:5], 0, v[164:165]
	s_mov_b32 s12, 0x2b4c000
	v_add_co_u32_e32 v12, vcc, s12, v6
	s_nop 1
	v_addc_co_u32_e32 v13, vcc, 0, v7, vcc
	global_load_dwordx4 v[16:19], v[12:13], off offset:256
	global_load_ushort v32, v[12:13], off offset:272
	s_mov_b32 s12, 0x2b4d000
	v_add_co_u32_e32 v12, vcc, s12, v6
	s_nop 1
	v_addc_co_u32_e32 v13, vcc, 0, v7, vcc
	global_load_dwordx4 v[20:23], v[12:13], off offset:256
	global_load_ushort v33, v[12:13], off offset:272
	s_mov_b32 s12, 0x2b4e000
	v_add_co_u32_e32 v12, vcc, s12, v6
	s_nop 1
	v_addc_co_u32_e32 v13, vcc, 0, v7, vcc
	global_load_dwordx4 v[24:27], v[12:13], off offset:256
	global_load_ushort v34, v[12:13], off offset:272
	s_mov_b32 s12, 0x2b4f000
	v_add_co_u32_e32 v12, vcc, s12, v6
	s_nop 1
	v_addc_co_u32_e32 v13, vcc, 0, v7, vcc
	global_load_dwordx4 v[28:31], v[12:13], off offset:256
	v_mov_b32_e32 v35, 0
	v_cmp_ne_u32_e32 vcc, s10, v4
	s_and_saveexec_b64 s[12:13], vcc
	global_load_ushort v35, v[12:13], off offset:272
	s_mov_b64 exec, s[12:13]
	s_branch .LBB0_732

; template <int BG>
; DEV void hyena_item_mfma(const Params& p, int g, int item, char* smem, int half) {
;     ...
;   if (half == 0) {
; #pragma unroll 8
;     for (int e = tid; e < 2 * L / 8; e += 256) ((uint4*)smem)[e] = ((const uint4*)RK)[e];
.LBB0_736:
	s_and_b64 vcc, exec, s[4:5]
	v_mov_b32_e32 v145, v164
	s_cbranch_vccz .LBB0_738
	v_readlane_b32 s4, v251, 8
	s_add_u32 s0, s4, s0
	v_readlane_b32 s4, v251, 9
	s_addc_u32 s1, s4, s1
	global_load_dwordx4 v[12:15], v8, s[0:1]
	v_add_u32_e32 v4, s14, v8
	v_mov_b32_e32 v145, v8
	v_or_b32_e32 v0, 0x1000, v8
	global_load_dwordx4 v[16:19], v0, s[0:1]
	v_or_b32_e32 v0, 0x2000, v8
	global_load_dwordx4 v[20:23], v0, s[0:1]
	v_or_b32_e32 v0, 0x3000, v8
	global_load_dwordx4 v[24:27], v0, s[0:1]
	v_or_b32_e32 v0, 0x4000, v8
	global_load_dwordx4 v[28:31], v0, s[0:1]
	v_or_b32_e32 v0, 0x5000, v8
	global_load_dwordx4 v[32:35], v0, s[0:1]
	v_or_b32_e32 v0, 0x6000, v8
	global_load_dwordx4 v[36:39], v0, s[0:1]
	v_or_b32_e32 v0, 0x7000, v8
	global_load_dwordx4 v[40:43], v0, s[0:1]
	s_waitcnt vmcnt(7)
	ds_write_b128 v4, v[12:15]
	s_waitcnt vmcnt(6)
	ds_write_b128 v4, v[16:19] offset:4096
	s_waitcnt vmcnt(5)
	ds_write_b128 v4, v[20:23] offset:8192
	s_waitcnt vmcnt(4)
	ds_write_b128 v4, v[24:27] offset:12288
	s_waitcnt vmcnt(3)
	ds_write_b128 v4, v[28:31] offset:16384
	s_waitcnt vmcnt(2)
	ds_write_b128 v4, v[32:35] offset:20480
	s_waitcnt vmcnt(1)
	ds_write_b128 v4, v[36:39] offset:24576
	s_waitcnt vmcnt(0)
	ds_write_b128 v4, v[40:43] offset:28672

; template <int BG>
; DEV void hyena_item_mfma(const Params& p, int g, int item, char* smem, int half) {
;     ...
;   __syncthreads();
;   if (half == 0) {
; #pragma unroll 8
;     for (int e = tid; e < 2 * L / 8; e += 256) ((uint4*)smem)[e] = ((const uint4*)RK)[e];
;   } else {
; #pragma unroll 4
;     for (int e = tid; e < 2 * L / 8; e += 256) {
;       const uint4 v = ((const uint4*)RK)[e];
;       const unsigned nx = (8 * e + 8 < 2 * L) ? (unsigned)RK[8 * e + 8] : 0u;
;       uint4 o;
;       o.x = (v.x >> 16) | (v.y << 16);
;       o.y = (v.y >> 16) | (v.z << 16);
;       o.z = (v.z >> 16) | (v.w << 16);
;       o.w = (v.w >> 16) | (nx << 16);
;       ((uint4*)(smem + RK1))[e] = o;
;     }
;   }
.LBB0_771:
	s_and_b64 vcc, exec, s[0:1]
	s_cbranch_vccz .LBB0_722
	s_lshl_b64 s[0:1], s[18:19], 14
	v_readlane_b32 s4, v251, 10
	s_waitcnt vmcnt(4)
	v_mov_b32_e32 v147, v202
	s_add_u32 s4, s4, s0
	v_readlane_b32 s0, v251, 11
	s_addc_u32 s5, s0, s1
	s_waitcnt vmcnt(1)
	v_and_b32_e32 v148, 0xff, v147
	v_lshlrev_b32_e32 v144, 4, v148
	v_mov_b32_e32 v145, v165
	s_movk_i32 s0, 0xff
	v_lshl_add_u64 v[4:5], s[4:5], 0, v[144:145]
	s_mov_b64 s[8:9], -1
	s_and_b64 vcc, exec, s[16:17]
	v_cmp_ne_u32_e64 s[0:1], s0, v148
	s_barrier
	s_cbranch_vccz .LBB0_776
	v_lshlrev_b32_e32 v7, 4, v148
	s_mov_b32 s10, 0x1000706
	v_add_u32_e32 v6, s14, v7
	global_load_dwordx4 v[12:15], v[4:5], off
	global_load_ushort v28, v7, s[4:5] offset:16
	v_or_b32_e32 v0, 0x1000, v7
	global_load_dwordx4 v[16:19], v0, s[4:5]
	global_load_ushort v29, v0, s[4:5] offset:16
	v_or_b32_e32 v0, 0x2000, v7
	global_load_dwordx4 v[20:23], v0, s[4:5]
	global_load_ushort v30, v0, s[4:5] offset:16
	v_or_b32_e32 v0, 0x300, v148
	v_lshlrev_b32_e32 v0, 4, v0
	global_load_dwordx4 v[24:27], v0, s[4:5]
	v_mov_b32_e32 v31, 0
	s_and_saveexec_b64 s[8:9], s[0:1]
	global_load_ushort v31, v0, s[4:5] offset:16
	s_mov_b64 exec, s[8:9]
	s_waitcnt vmcnt(0)
	v_perm_b32 v8, v12, v13, s10
	v_perm_b32 v9, v13, v14, s10
	v_perm_b32 v10, v14, v15, s10
	v_perm_b32 v11, v15, v28, s10
	ds_write_b128 v6, v[8:11] offset:16448
	v_perm_b32 v8, v16, v17, s10
	v_perm_b32 v9, v17, v18, s10
	v_perm_b32 v10, v18, v19, s10
	v_perm_b32 v11, v19, v29, s10
	ds_write_b128 v6, v[8:11] offset:20544
	v_perm_b32 v8, v20, v21, s10
	v_perm_b32 v9, v21, v22, s10
	v_perm_b32 v10, v22, v23, s10
	v_perm_b32 v11, v23, v30, s10
	ds_write_b128 v6, v[8:11] offset:24640
	v_perm_b32 v8, v24, v25, s10
	v_perm_b32 v9, v25, v26, s10
	v_perm_b32 v10, v26, v27, s10
	v_perm_b32 v11, v27, v31, s10
	ds_write_b128 v6, v[8:11] offset:28736
	v_lshlrev_b32_e32 v146, 3, v148
	s_mov_b64 s[8:9], 0
.LBB0_776:
	s_and_b64 vcc, exec, s[8:9]
	s_cbranch_vccz .LBB0_778
	global_load_dwordx4 v[12:15], v[4:5], off
	v_lshlrev_b32_e32 v6, 4, v148
	v_add_u32_e32 v7, s14, v6
	v_lshlrev_b32_e32 v146, 3, v148
	v_or_b32_e32 v0, 0x1000, v6
	global_load_dwordx4 v[16:19], v0, s[4:5]
	v_or_b32_e32 v0, 0x2000, v6
	global_load_dwordx4 v[20:23], v0, s[4:5]
	v_or_b32_e32 v0, 0x3000, v6
	global_load_dwordx4 v[24:27], v0, s[4:5]
	s_waitcnt vmcnt(3)
	ds_write_b128 v7, v[12:15]
	s_waitcnt vmcnt(2)
	ds_write_b128 v7, v[16:19] offset:4096
	s_waitcnt vmcnt(1)
	ds_write_b128 v7, v[20:23] offset:8192
	s_waitcnt vmcnt(0)
	ds_write_b128 v7, v[24:27] offset:12288
